# mixing: wait fixes + pass-C tail loads hoisted + DPP gate scans
# baseline (speedup 1.0000x reference)
.LBB0_534:
	s_or_b64 exec, exec, s[14:15]
	s_waitcnt vmcnt(9)
	ds_write_b128 v146, v[72:75] offset:34816
	s_waitcnt vmcnt(8)
	ds_write_b128 v146, v[68:71] offset:34832
	s_mov_b64 s[14:15], exec
	v_readlane_b32 s16, v254, 47
	v_readlane_b32 s17, v254, 48
	s_and_b64 s[16:17], s[14:15], s[16:17]
	s_mov_b64 exec, s[16:17]
	ds_write_b128 v166, v[44:47] offset:54272
	s_or_b64 exec, exec, s[14:15]
	s_mov_b64 s[14:15], exec
	v_readlane_b32 s16, v254, 49
	v_readlane_b32 s17, v254, 50
	s_and_b64 s[16:17], s[14:15], s[16:17]
	s_mov_b64 exec, s[16:17]
	ds_write_b128 v167, v[40:43] offset:54272
	s_or_b64 exec, exec, s[14:15]
	s_mov_b64 s[14:15], exec
	v_readlane_b32 s16, v254, 51
	v_readlane_b32 s17, v254, 52
	s_and_b64 s[16:17], s[14:15], s[16:17]
	s_mov_b64 exec, s[16:17]
	ds_write_b128 v168, v[56:59] offset:54272
	s_or_b64 exec, exec, s[14:15]
	s_mov_b64 s[14:15], exec
	v_readlane_b32 s16, v254, 53
	v_readlane_b32 s17, v254, 54
	s_and_b64 s[16:17], s[14:15], s[16:17]
	s_mov_b64 exec, s[16:17]
	ds_write_b128 v169, v[48:51] offset:54272
	s_or_b64 exec, exec, s[14:15]
	s_and_saveexec_b64 s[14:15], s[58:59]
	ds_write_b128 v170, v[64:67] offset:54272
	s_or_b64 exec, exec, s[14:15]
	ds_read_b128 v[40:43], v147
	ds_read_b128 v[44:47], v147 offset:16
	ds_read_b128 v[48:51], v148
	ds_read_b128 v[56:59], v148 offset:16
	v_lshlrev_b32_e32 v64, 16, v52
	v_and_b32_e32 v65, 0xffff0000, v52
	v_lshlrev_b32_e32 v52, 16, v53
	v_and_b32_e32 v53, 0xffff0000, v53
	s_waitcnt lgkmcnt(1)
	v_pk_fma_f32 v[48:49], v[48:49], v[64:65], v[40:41]
	v_pk_fma_f32 v[50:51], v[50:51], v[52:53], v[42:43]
	v_lshlrev_b32_e32 v40, 16, v54
	v_and_b32_e32 v41, 0xffff0000, v54
	v_lshlrev_b32_e32 v42, 16, v55
	v_and_b32_e32 v43, 0xffff0000, v55
	s_waitcnt lgkmcnt(0)
	v_pk_fma_f32 v[52:53], v[56:57], v[40:41], v[44:45]
	v_pk_fma_f32 v[54:55], v[58:59], v[42:43], v[46:47]
	ds_read_b128 v[44:47], v148 offset:512
	v_lshlrev_b32_e32 v40, 16, v60
	v_and_b32_e32 v41, 0xffff0000, v60
	v_lshlrev_b32_e32 v42, 16, v61
	v_and_b32_e32 v43, 0xffff0000, v61
	s_waitcnt lgkmcnt(0)
	v_pk_fma_f32 v[56:57], v[46:47], v[42:43], v[50:51]
	v_pk_fma_f32 v[58:59], v[44:45], v[40:41], v[48:49]
	ds_read_b128 v[48:51], v148 offset:528
	v_lshlrev_b32_e32 v44, 16, v62
	v_and_b32_e32 v45, 0xffff0000, v62
	v_lshlrev_b32_e32 v46, 16, v63
	v_and_b32_e32 v47, 0xffff0000, v63
	s_waitcnt lgkmcnt(0)
	v_pk_fma_f32 v[60:61], v[50:51], v[46:47], v[54:55]
	v_pk_fma_f32 v[62:63], v[48:49], v[44:45], v[52:53]
	ds_read_b128 v[52:55], v148 offset:1024
	v_lshlrev_b32_e32 v48, 16, v36
	v_and_b32_e32 v49, 0xffff0000, v36
	v_lshlrev_b32_e32 v50, 16, v37
	v_and_b32_e32 v51, 0xffff0000, v37
	s_waitcnt lgkmcnt(0)
	v_pk_fma_f32 v[64:65], v[52:53], v[48:49], v[58:59]
	v_pk_fma_f32 v[66:67], v[54:55], v[50:51], v[56:57]
	ds_read_b128 v[52:55], v148 offset:1040
	v_lshlrev_b32_e32 v36, 16, v38
	v_and_b32_e32 v37, 0xffff0000, v38
	v_lshlrev_b32_e32 v38, 16, v39
	v_and_b32_e32 v39, 0xffff0000, v39
	s_waitcnt lgkmcnt(0)
	v_pk_fma_f32 v[68:69], v[54:55], v[38:39], v[60:61]
	ds_read_b128 v[58:61], v148 offset:1536
	v_lshlrev_b32_e32 v54, 16, v32
	v_and_b32_e32 v55, 0xffff0000, v32
	v_lshlrev_b32_e32 v56, 16, v33
	v_and_b32_e32 v57, 0xffff0000, v33
	s_waitcnt lgkmcnt(0)
	v_pk_fma_f32 v[66:67], v[60:61], v[56:57], v[66:67]
	v_pk_fma_f32 v[64:65], v[58:59], v[54:55], v[64:65]
	ds_read_b128 v[58:61], v148 offset:1552
	v_lshlrev_b32_e32 v32, 16, v35
	v_and_b32_e32 v33, 0xffff0000, v35
	v_pk_fma_f32 v[62:63], v[52:53], v[36:37], v[62:63]
	v_lshlrev_b32_e32 v52, 16, v34
	v_and_b32_e32 v53, 0xffff0000, v34
	s_waitcnt lgkmcnt(0)
	v_pk_fma_f32 v[34:35], v[60:61], v[32:33], v[68:69]
	v_mul_f32_e32 v60, 0xbfb8aa3b, v64
	v_mul_f32_e32 v61, 0xbfb8aa3b, v65
	v_exp_f32_e32 v60, v60
	v_exp_f32_e32 v61, v61
	v_pk_fma_f32 v[58:59], v[58:59], v[52:53], v[62:63]
	s_mov_b32 s14, 0x3db504f3
	v_add_f32_e32 v60, 1.0, v60
	v_add_f32_e32 v61, 1.0, v61
	v_rcp_f32_e32 v60, v60
	v_rcp_f32_e32 v61, v61
	v_mul_f32_e32 v62, 0xbfb8aa3b, v66
	v_mul_f32_e32 v63, 0xbfb8aa3b, v67
	v_exp_f32_e32 v62, v62
	v_pk_mul_f32 v[60:61], v[64:65], v[60:61]
	v_mul_f32_e32 v64, 0xbfb8aa3b, v58
	v_mul_f32_e32 v65, 0xbfb8aa3b, v59
	v_exp_f32_e32 v64, v64
	v_exp_f32_e32 v65, v65
	v_exp_f32_e32 v63, v63
	v_add_f32_e32 v62, 1.0, v62
	v_add_f32_e32 v64, 1.0, v64
	v_add_f32_e32 v65, 1.0, v65
	v_rcp_f32_e32 v64, v64
	v_rcp_f32_e32 v65, v65
	v_add_f32_e32 v63, 1.0, v63
	v_rcp_f32_e32 v62, v62
	v_rcp_f32_e32 v63, v63
	v_pk_mul_f32 v[58:59], v[58:59], v[64:65]
	v_pk_mul_f32 v[60:61], v[60:61], s[14:15] op_sel_hi:[1,0]
	v_pk_mul_f32 v[64:65], v[58:59], s[14:15] op_sel_hi:[1,0]
	v_mul_f32_e32 v58, 0xbfb8aa3b, v34
	v_mul_f32_e32 v59, 0xbfb8aa3b, v35
	v_exp_f32_e32 v58, v58
	v_exp_f32_e32 v59, v59
	v_pk_mul_f32 v[62:63], v[66:67], v[62:63]
	s_and_b64 vcc, exec, s[12:13]
	v_add_f32_e32 v58, 1.0, v58
	v_add_f32_e32 v59, 1.0, v59
	v_rcp_f32_e32 v58, v58
	v_rcp_f32_e32 v59, v59
	v_pk_mul_f32 v[62:63], v[62:63], s[14:15] op_sel_hi:[1,0]
	v_pk_mul_f32 v[34:35], v[34:35], v[58:59]
	s_nop 0
	v_pk_mul_f32 v[34:35], v[34:35], s[14:15] op_sel_hi:[1,0]
	v_cvt_pk_bf16_f32 v58, v60, v61
	v_cvt_pk_bf16_f32 v59, v62, v63
	v_cvt_pk_bf16_f32 v60, v64, v65
	v_cvt_pk_bf16_f32 v61, v34, v35
	ds_write_b128 v171, v[58:61]
	ds_read_b128 v[58:61], v147
	ds_read_b128 v[62:65], v147 offset:16
	ds_read_b128 v[66:69], v148
	ds_read_b128 v[70:73], v148 offset:16
	s_waitcnt lgkmcnt(1)
	v_pk_fma_f32 v[34:35], v[66:67], v[40:41], v[58:59]
	v_pk_fma_f32 v[58:59], v[68:69], v[42:43], v[60:61]
	ds_read_b128 v[40:43], v148 offset:512
	s_waitcnt lgkmcnt(1)
	v_pk_fma_f32 v[44:45], v[70:71], v[44:45], v[62:63]
	v_pk_fma_f32 v[46:47], v[72:73], v[46:47], v[64:65]
	s_waitcnt lgkmcnt(0)
	v_pk_fma_f32 v[50:51], v[42:43], v[50:51], v[58:59]
	v_pk_fma_f32 v[48:49], v[40:41], v[48:49], v[34:35]
	ds_read_b128 v[40:43], v148 offset:528
	s_waitcnt lgkmcnt(0)
	v_pk_fma_f32 v[40:41], v[40:41], v[36:37], v[44:45]
	ds_read_b128 v[34:37], v148 offset:1024
	v_pk_fma_f32 v[38:39], v[42:43], v[38:39], v[46:47]
	s_waitcnt lgkmcnt(0)
	v_pk_fma_f32 v[42:43], v[34:35], v[54:55], v[48:49]
	v_pk_fma_f32 v[44:45], v[36:37], v[56:57], v[50:51]
	ds_read_b128 v[34:37], v148 offset:1040
	s_waitcnt lgkmcnt(0)
	v_pk_fma_f32 v[40:41], v[34:35], v[52:53], v[40:41]
	v_pk_fma_f32 v[36:37], v[36:37], v[32:33], v[38:39]
	ds_read_b128 v[32:35], v148 offset:1536
	v_lshlrev_b32_e32 v38, 16, v28
	v_and_b32_e32 v39, 0xffff0000, v28
	v_lshlrev_b32_e32 v28, 16, v29
	v_and_b32_e32 v29, 0xffff0000, v29
	s_waitcnt lgkmcnt(0)
	v_pk_fma_f32 v[34:35], v[34:35], v[28:29], v[44:45]
	v_pk_fma_f32 v[32:33], v[32:33], v[38:39], v[42:43]
	v_lshlrev_b32_e32 v38, 16, v30
	v_and_b32_e32 v39, 0xffff0000, v30
	v_lshlrev_b32_e32 v42, 16, v31
	v_and_b32_e32 v43, 0xffff0000, v31
	ds_read_b128 v[28:31], v148 offset:1552
	v_lshlrev_b32_e32 v44, 16, v24
	v_and_b32_e32 v45, 0xffff0000, v24
	v_lshlrev_b32_e32 v24, 16, v25
	v_and_b32_e32 v25, 0xffff0000, v25
	s_waitcnt lgkmcnt(0)
	v_pk_fma_f32 v[30:31], v[30:31], v[42:43], v[36:37]
	v_mul_f32_e32 v36, 0xbfb8aa3b, v32
	v_mul_f32_e32 v37, 0xbfb8aa3b, v33
	v_exp_f32_e32 v36, v36
	v_exp_f32_e32 v37, v37
	v_pk_fma_f32 v[28:29], v[28:29], v[38:39], v[40:41]
	v_add_f32_e32 v36, 1.0, v36
	v_add_f32_e32 v37, 1.0, v37
	v_rcp_f32_e32 v36, v36
	v_rcp_f32_e32 v37, v37
	s_nop 0
	v_pk_mul_f32 v[32:33], v[32:33], v[36:37]
	v_mul_f32_e32 v36, 0xbfb8aa3b, v34
	v_mul_f32_e32 v37, 0xbfb8aa3b, v35
	v_exp_f32_e32 v36, v36
	v_exp_f32_e32 v37, v37
	v_pk_mul_f32 v[32:33], v[32:33], s[14:15] op_sel_hi:[1,0]
	v_add_f32_e32 v36, 1.0, v36
	v_add_f32_e32 v37, 1.0, v37
	v_rcp_f32_e32 v36, v36
	v_rcp_f32_e32 v37, v37
	s_nop 0
	v_pk_mul_f32 v[34:35], v[34:35], v[36:37]
	v_mul_f32_e32 v36, 0xbfb8aa3b, v28
	v_mul_f32_e32 v37, 0xbfb8aa3b, v29
	v_exp_f32_e32 v36, v36
	v_exp_f32_e32 v37, v37
	v_pk_mul_f32 v[34:35], v[34:35], s[14:15] op_sel_hi:[1,0]
	v_add_f32_e32 v36, 1.0, v36
	v_add_f32_e32 v37, 1.0, v37
	v_rcp_f32_e32 v36, v36
	v_rcp_f32_e32 v37, v37
	s_nop 0
	v_pk_mul_f32 v[28:29], v[28:29], v[36:37]
	s_nop 0
	v_pk_mul_f32 v[36:37], v[28:29], s[14:15] op_sel_hi:[1,0]
	v_mul_f32_e32 v28, 0xbfb8aa3b, v30
	v_mul_f32_e32 v29, 0xbfb8aa3b, v31
	v_exp_f32_e32 v28, v28
	v_exp_f32_e32 v29, v29
	v_add_f32_e32 v28, 1.0, v28
	v_add_f32_e32 v29, 1.0, v29
	v_rcp_f32_e32 v28, v28
	v_rcp_f32_e32 v29, v29
	s_nop 0
	v_pk_mul_f32 v[28:29], v[30:31], v[28:29]
	s_nop 0
	v_pk_mul_f32 v[38:39], v[28:29], s[14:15] op_sel_hi:[1,0]
	v_cvt_pk_bf16_f32 v28, v32, v33
	v_cvt_pk_bf16_f32 v29, v34, v35
	v_cvt_pk_bf16_f32 v30, v36, v37
	v_cvt_pk_bf16_f32 v31, v38, v39
	ds_write_b128 v171, v[28:31] offset:272
	ds_read_b128 v[28:31], v147 offset:512
	ds_read_b128 v[32:35], v147 offset:528
	ds_read_b128 v[36:39], v148 offset:2048
	ds_read_b128 v[40:43], v148 offset:2064
	s_waitcnt lgkmcnt(1)
	v_pk_fma_f32 v[30:31], v[38:39], v[24:25], v[30:31]
	v_lshlrev_b32_e32 v24, 16, v26
	v_and_b32_e32 v25, 0xffff0000, v26
	v_lshlrev_b32_e32 v26, 16, v27
	v_and_b32_e32 v27, 0xffff0000, v27
	v_pk_fma_f32 v[36:37], v[36:37], v[44:45], v[28:29]
	s_waitcnt lgkmcnt(0)
	v_pk_fma_f32 v[34:35], v[42:43], v[26:27], v[34:35]
	ds_read_b128 v[26:29], v148 offset:2560
	v_pk_fma_f32 v[32:33], v[40:41], v[24:25], v[32:33]
	v_lshlrev_b32_e32 v24, 16, v20
	v_and_b32_e32 v25, 0xffff0000, v20
	v_lshlrev_b32_e32 v20, 16, v21
	v_and_b32_e32 v21, 0xffff0000, v21
	s_waitcnt lgkmcnt(0)
	v_pk_fma_f32 v[38:39], v[28:29], v[20:21], v[30:31]
	ds_read_b128 v[28:31], v148 offset:2576
	v_pk_fma_f32 v[36:37], v[26:27], v[24:25], v[36:37]
	v_lshlrev_b32_e32 v26, 16, v22
	v_and_b32_e32 v27, 0xffff0000, v22
	v_lshlrev_b32_e32 v22, 16, v23
	v_and_b32_e32 v23, 0xffff0000, v23
	s_waitcnt lgkmcnt(0)
	v_pk_fma_f32 v[40:41], v[30:31], v[22:23], v[34:35]
	v_pk_fma_f32 v[42:43], v[28:29], v[26:27], v[32:33]
	ds_read_b128 v[32:35], v148 offset:3072
	v_lshlrev_b32_e32 v28, 16, v16
	v_and_b32_e32 v29, 0xffff0000, v16
	v_lshlrev_b32_e32 v30, 16, v17
	v_and_b32_e32 v31, 0xffff0000, v17
	s_waitcnt lgkmcnt(0)
	v_pk_fma_f32 v[44:45], v[32:33], v[28:29], v[36:37]
	v_pk_fma_f32 v[46:47], v[34:35], v[30:31], v[38:39]
	ds_read_b128 v[32:35], v148 offset:3088
	v_lshlrev_b32_e32 v16, 16, v18
	v_and_b32_e32 v17, 0xffff0000, v18
	v_lshlrev_b32_e32 v18, 16, v19
	v_and_b32_e32 v19, 0xffff0000, v19
	s_waitcnt lgkmcnt(0)
	v_pk_fma_f32 v[48:49], v[34:35], v[18:19], v[40:41]
	ds_read_b128 v[38:41], v148 offset:3584
	v_lshlrev_b32_e32 v34, 16, v12
	v_and_b32_e32 v35, 0xffff0000, v12
	v_lshlrev_b32_e32 v36, 16, v13
	v_and_b32_e32 v37, 0xffff0000, v13
	s_waitcnt lgkmcnt(0)
	v_pk_fma_f32 v[46:47], v[40:41], v[36:37], v[46:47]
	v_pk_fma_f32 v[44:45], v[38:39], v[34:35], v[44:45]
	ds_read_b128 v[38:41], v148 offset:3600
	v_lshlrev_b32_e32 v12, 16, v15
	v_and_b32_e32 v13, 0xffff0000, v15
	v_pk_fma_f32 v[42:43], v[32:33], v[16:17], v[42:43]
	v_lshlrev_b32_e32 v32, 16, v14
	v_and_b32_e32 v33, 0xffff0000, v14
	s_waitcnt lgkmcnt(0)
	v_pk_fma_f32 v[14:15], v[40:41], v[12:13], v[48:49]
	v_mul_f32_e32 v40, 0xbfb8aa3b, v44
	v_mul_f32_e32 v41, 0xbfb8aa3b, v45
	v_exp_f32_e32 v40, v40
	v_exp_f32_e32 v41, v41
	v_pk_fma_f32 v[38:39], v[38:39], v[32:33], v[42:43]
	v_mul_f32_e32 v42, 0xbfb8aa3b, v46
	v_add_f32_e32 v40, 1.0, v40
	v_add_f32_e32 v41, 1.0, v41
	v_rcp_f32_e32 v40, v40
	v_rcp_f32_e32 v41, v41
	v_mul_f32_e32 v43, 0xbfb8aa3b, v47
	v_exp_f32_e32 v42, v42
	v_exp_f32_e32 v43, v43
	v_pk_mul_f32 v[40:41], v[44:45], v[40:41]
	v_mul_f32_e32 v44, 0xbfb8aa3b, v38
	v_mul_f32_e32 v45, 0xbfb8aa3b, v39
	v_exp_f32_e32 v44, v44
	v_exp_f32_e32 v45, v45
	v_add_f32_e32 v42, 1.0, v42
	v_add_f32_e32 v43, 1.0, v43
	v_add_f32_e32 v44, 1.0, v44
	v_add_f32_e32 v45, 1.0, v45
	v_rcp_f32_e32 v44, v44
	v_rcp_f32_e32 v45, v45
	v_rcp_f32_e32 v42, v42
	v_rcp_f32_e32 v43, v43
	v_pk_mul_f32 v[44:45], v[38:39], v[44:45]
	v_mul_f32_e32 v38, 0xbfb8aa3b, v14
	v_mul_f32_e32 v39, 0xbfb8aa3b, v15
	v_exp_f32_e32 v38, v38
	v_exp_f32_e32 v39, v39
	v_pk_mul_f32 v[42:43], v[46:47], v[42:43]
	v_add_f32_e32 v38, 1.0, v38
	v_add_f32_e32 v39, 1.0, v39
	v_rcp_f32_e32 v38, v38
	v_rcp_f32_e32 v39, v39
	s_nop 0
	v_pk_mul_f32 v[14:15], v[14:15], v[38:39]
	v_cvt_pk_bf16_f32 v38, v40, v41
	v_cvt_pk_bf16_f32 v39, v42, v43
	v_cvt_pk_bf16_f32 v40, v44, v45
	v_cvt_pk_bf16_f32 v41, v14, v15
	ds_write_b128 v171, v[38:41] offset:17408
	ds_read_b128 v[38:41], v147 offset:512
	ds_read_b128 v[42:45], v147 offset:528
	ds_read_b128 v[46:49], v148 offset:2048
	ds_read_b128 v[50:53], v148 offset:2064
	s_waitcnt lgkmcnt(1)
	v_pk_fma_f32 v[14:15], v[46:47], v[24:25], v[38:39]
	v_pk_fma_f32 v[24:25], v[48:49], v[20:21], v[40:41]
	s_waitcnt lgkmcnt(0)
	v_pk_fma_f32 v[38:39], v[52:53], v[22:23], v[44:45]
	ds_read_b128 v[20:23], v148 offset:2560
	v_pk_fma_f32 v[26:27], v[50:51], v[26:27], v[42:43]
	s_waitcnt lgkmcnt(0)
	v_pk_fma_f32 v[24:25], v[22:23], v[30:31], v[24:25]
	v_pk_fma_f32 v[28:29], v[20:21], v[28:29], v[14:15]
	ds_read_b128 v[20:23], v148 offset:2576
	s_waitcnt lgkmcnt(0)
	v_pk_fma_f32 v[20:21], v[20:21], v[16:17], v[26:27]
	ds_read_b128 v[14:17], v148 offset:3072
	v_pk_fma_f32 v[18:19], v[22:23], v[18:19], v[38:39]
	s_waitcnt lgkmcnt(0)
	v_pk_fma_f32 v[22:23], v[14:15], v[34:35], v[28:29]
	v_pk_fma_f32 v[24:25], v[16:17], v[36:37], v[24:25]
	ds_read_b128 v[14:17], v148 offset:3088
	s_waitcnt lgkmcnt(0)
	v_pk_fma_f32 v[20:21], v[14:15], v[32:33], v[20:21]
	v_pk_fma_f32 v[16:17], v[16:17], v[12:13], v[18:19]
	ds_read_b128 v[12:15], v148 offset:3584
	v_lshlrev_b32_e32 v18, 16, v8
	v_and_b32_e32 v19, 0xffff0000, v8
	v_lshlrev_b32_e32 v8, 16, v9
	v_and_b32_e32 v9, 0xffff0000, v9
	s_waitcnt lgkmcnt(0)
	v_pk_fma_f32 v[14:15], v[14:15], v[8:9], v[24:25]
	v_pk_fma_f32 v[12:13], v[12:13], v[18:19], v[22:23]
	v_lshlrev_b32_e32 v18, 16, v10
	v_and_b32_e32 v19, 0xffff0000, v10
	v_lshlrev_b32_e32 v22, 16, v11
	v_and_b32_e32 v23, 0xffff0000, v11
	ds_read_b128 v[8:11], v148 offset:3600
	s_waitcnt lgkmcnt(0)
	v_pk_fma_f32 v[10:11], v[10:11], v[22:23], v[16:17]
	v_mul_f32_e32 v16, 0xbfb8aa3b, v12
	v_mul_f32_e32 v17, 0xbfb8aa3b, v13
	v_exp_f32_e32 v16, v16
	v_exp_f32_e32 v17, v17
	v_pk_fma_f32 v[8:9], v[8:9], v[18:19], v[20:21]
	v_add_f32_e32 v16, 1.0, v16
	v_add_f32_e32 v17, 1.0, v17
	v_rcp_f32_e32 v16, v16
	v_rcp_f32_e32 v17, v17
	s_nop 0
	v_pk_mul_f32 v[12:13], v[12:13], v[16:17]
	v_mul_f32_e32 v16, 0xbfb8aa3b, v14
	v_mul_f32_e32 v17, 0xbfb8aa3b, v15
	v_exp_f32_e32 v16, v16
	v_exp_f32_e32 v17, v17
	v_add_f32_e32 v16, 1.0, v16
	v_add_f32_e32 v17, 1.0, v17
	v_rcp_f32_e32 v16, v16
	v_rcp_f32_e32 v17, v17
	s_nop 0
	v_pk_mul_f32 v[14:15], v[14:15], v[16:17]
	v_mul_f32_e32 v16, 0xbfb8aa3b, v8
	v_mul_f32_e32 v17, 0xbfb8aa3b, v9
	v_exp_f32_e32 v16, v16
	v_exp_f32_e32 v17, v17
	v_add_f32_e32 v16, 1.0, v16
	v_add_f32_e32 v17, 1.0, v17
	v_rcp_f32_e32 v16, v16
	v_rcp_f32_e32 v17, v17
	s_nop 0
	v_pk_mul_f32 v[16:17], v[8:9], v[16:17]
	v_mul_f32_e32 v8, 0xbfb8aa3b, v10
	v_mul_f32_e32 v9, 0xbfb8aa3b, v11
	v_exp_f32_e32 v8, v8
	v_exp_f32_e32 v9, v9
	v_add_f32_e32 v8, 1.0, v8
	v_add_f32_e32 v9, 1.0, v9
	v_rcp_f32_e32 v8, v8
	v_rcp_f32_e32 v9, v9
	s_nop 0
	v_pk_mul_f32 v[18:19], v[10:11], v[8:9]
	v_cvt_pk_bf16_f32 v8, v12, v13
	v_cvt_pk_bf16_f32 v9, v14, v15
	v_cvt_pk_bf16_f32 v10, v16, v17
	v_cvt_pk_bf16_f32 v11, v18, v19
	ds_write_b128 v171, v[8:11] offset:17680
	s_cbranch_vccnz .LBB0_546
	v_mov_b32_e32 v10, v77
	s_ashr_i32 s9, s8, 31
	s_lshl_b64 s[12:13], s[8:9], 2
	v_readlane_b32 s9, v251, 53
	s_add_u32 s12, s9, s12
	v_readlane_b32 s9, v251, 54
	s_addc_u32 s13, s9, s13
	s_nop 0
	global_load_dword v14, v181, s[12:13]
	s_nop 1
	v_add_f32_dpp v10, v10, v10 row_shr:1 row_mask:0xf bank_mask:0xf
	s_nop 1
	v_add_f32_dpp v10, v10, v10 row_shr:2 row_mask:0xf bank_mask:0xf
	s_nop 1
	v_add_f32_dpp v10, v10, v10 row_shr:4 row_mask:0xf bank_mask:0xf
	s_nop 1
	v_add_f32_dpp v10, v10, v10 row_shr:8 row_mask:0xf bank_mask:0xf
	s_nop 1
	v_add_f32_dpp v10, v10, v10 row_bcast:15 row_mask:0xa bank_mask:0xf
	s_nop 1
	v_add_f32_dpp v10, v10, v10 row_bcast:31 row_mask:0xc bank_mask:0xf
	v_sub_f32_e32 v15, v76, v10
	ds_write2st64_b32 v149, v10, v15 offset1:1
	v_mov_b32_e32 v9, v15
	s_nop 1
	v_max_f32_dpp v9, v9, v9 row_shr:1 row_mask:0xf bank_mask:0xf
	s_nop 1
	v_max_f32_dpp v9, v9, v9 row_shr:2 row_mask:0xf bank_mask:0xf
	s_nop 1
	v_max_f32_dpp v9, v9, v9 row_shr:4 row_mask:0xf bank_mask:0xf
	s_nop 1
	v_max_f32_dpp v9, v9, v9 row_shr:8 row_mask:0xf bank_mask:0xf
	s_nop 1
	v_max_f32_dpp v9, v9, v9 row_bcast:15 row_mask:0xa bank_mask:0xf
	s_nop 1
	v_max_f32_dpp v9, v9, v9 row_bcast:31 row_mask:0xc bank_mask:0xf
	v_max_f32_e32 v8, v9, v9
	s_waitcnt vmcnt(0)
	v_max_f32_e32 v11, v14, v14
	v_max_f32_e32 v8, v8, v11
	v_add_f32_e32 v8, v10, v8
	v_add_f32_e32 v9, v14, v10
	v_sub_f32_e32 v9, v9, v8
	v_mul_f32_e32 v9, 0x3fb8aa3b, v9
	v_exp_f32_e32 v9, v9
	ds_write2st64_b32 v149, v8, v9 offset0:2 offset1:3
	v_mul_f32_e32 v8, 0xbfb8aa3b, v8
	v_exp_f32_e32 v8, v8
	ds_write_b32 v149, v8 offset:1280
